# norm1/norm2 output stage: 12 gamma/shift/scale loads per token issued together; barrier census loads batched
# speedup vs baseline: 1.0114x; 1.0005x over previous
.LBB0_89:
	s_or_b64 exec, exec, s[0:1]
	s_waitcnt vmcnt(3)
	v_mov_b32_e32 v96, v63
	s_waitcnt vmcnt(2)
	v_mov_b32_e32 v97, v59
	v_mov_b32_e32 v94, v62
	v_mov_b32_e32 v95, v58
	v_pk_mul_f32 v[96:97], v[96:97], v[96:97]
	s_waitcnt vmcnt(1)
	v_mov_b32_e32 v98, v55
	v_pk_fma_f32 v[94:95], v[94:95], v[94:95], v[96:97]
	v_mov_b32_e32 v96, v64
	v_mov_b32_e32 v97, v60
	v_pk_fma_f32 v[94:95], v[96:97], v[96:97], v[94:95]
	v_mov_b32_e32 v96, v65
	v_mov_b32_e32 v97, v61
	s_waitcnt vmcnt(0)
	v_mov_b32_e32 v99, v51
	v_pk_fma_f32 v[94:95], v[96:97], v[96:97], v[94:95]
	v_mov_b32_e32 v96, v54
	v_mov_b32_e32 v97, v50
	v_pk_mul_f32 v[98:99], v[98:99], v[98:99]
	v_add_f32_e32 v0, v94, v95
	v_pk_fma_f32 v[96:97], v[96:97], v[96:97], v[98:99]
	v_mov_b32_e32 v98, v56
	v_mov_b32_e32 v99, v52
	v_pk_fma_f32 v[96:97], v[98:99], v[98:99], v[96:97]
	v_mov_b32_e32 v98, v57
	v_mov_b32_e32 v99, v53
	v_pk_fma_f32 v[96:97], v[98:99], v[98:99], v[96:97]
	v_pk_mul_f32 v[94:95], v[46:47], v[46:47]
	v_add_f32_e32 v0, v0, v96
	v_add_f32_e32 v0, v0, v97
	ds_bpermute_b32 v67, v69, v0
	v_pk_mul_f32 v[98:99], v[42:43], v[42:43]
	v_pk_mul_f32 v[96:97], v[48:49], v[48:49]
	v_pk_mul_f32 v[102:103], v[44:45], v[44:45]
	v_pk_mul_f32 v[104:105], v[38:39], v[38:39]
	s_waitcnt lgkmcnt(0)
	v_add_f32_e32 v0, v0, v67
	ds_bpermute_b32 v67, v73, v0
	v_pk_mul_f32 v[106:107], v[40:41], v[40:41]
	v_pk_mul_f32 v[110:111], v[34:35], v[34:35]
	v_pk_mul_f32 v[114:115], v[36:37], v[36:37]
	v_pk_mul_f32 v[116:117], v[20:21], v[20:21]
	s_waitcnt lgkmcnt(0)
	v_add_f32_e32 v0, v0, v67
	ds_bpermute_b32 v67, v75, v0
	v_pk_mul_f32 v[118:119], v[4:5], v[4:5]
	s_movk_i32 s0, 0x1fff
	v_cmp_lt_i32_e64 s[0:1], s0, v66
	s_waitcnt lgkmcnt(0)
	v_add_f32_e32 v0, v0, v67
	ds_bpermute_b32 v67, v77, v0
	s_waitcnt lgkmcnt(0)
	v_add_f32_e32 v0, v0, v67
	ds_bpermute_b32 v67, v101, v0
	s_waitcnt lgkmcnt(0)
	v_add_f32_e32 v0, v0, v67
	v_add_f32_e32 v67, v95, v94
	v_add_f32_e32 v94, v99, v98
	v_add_f32_e32 v67, v96, v67
	v_add_f32_e32 v94, v102, v94
	v_add_f32_e32 v67, v97, v67
	v_add_f32_e32 v94, v103, v94
	v_add_f32_e32 v67, v94, v67
	v_add_f32_e32 v94, v105, v104
	v_add_f32_e32 v94, v106, v94
	v_add_f32_e32 v94, v107, v94
	v_add_f32_e32 v67, v94, v67
	v_add_f32_e32 v94, v111, v110
	v_add_f32_e32 v94, v114, v94
	v_add_f32_e32 v94, v115, v94
	v_add_f32_e32 v67, v94, v67
	ds_bpermute_b32 v94, v69, v67
	v_pk_mul_f32 v[98:99], v[26:27], v[26:27]
	v_pk_mul_f32 v[96:97], v[32:33], v[32:33]
	v_pk_mul_f32 v[102:103], v[28:29], v[28:29]
	v_pk_mul_f32 v[104:105], v[22:23], v[22:23]
	s_waitcnt lgkmcnt(0)
	v_add_f32_e32 v67, v67, v94
	ds_bpermute_b32 v94, v73, v67
	v_pk_mul_f32 v[106:107], v[24:25], v[24:25]
	v_pk_mul_f32 v[110:111], v[18:19], v[18:19]
	ds_bpermute_b32 v100, v108, v0
	s_waitcnt lgkmcnt(1)
	v_add_f32_e32 v67, v67, v94
	ds_bpermute_b32 v94, v75, v67
	s_waitcnt lgkmcnt(1)
	v_add_f32_e32 v0, v0, v100
	v_fmamk_f32 v0, v0, 0x3a800000, v213
	s_waitcnt lgkmcnt(0)
	v_add_f32_e32 v67, v67, v94
	ds_bpermute_b32 v94, v77, v67
	s_waitcnt lgkmcnt(0)
	v_add_f32_e32 v67, v67, v94
	ds_bpermute_b32 v94, v101, v67
	s_waitcnt lgkmcnt(0)
	v_add_f32_e32 v113, v67, v94
	v_pk_mul_f32 v[94:95], v[30:31], v[30:31]
	ds_bpermute_b32 v114, v108, v113
	v_add_f32_e32 v67, v95, v94
	v_add_f32_e32 v94, v99, v98
	v_add_f32_e32 v67, v96, v67
	v_add_f32_e32 v94, v102, v94
	v_add_f32_e32 v67, v97, v67
	v_add_f32_e32 v94, v103, v94
	v_add_f32_e32 v67, v94, v67
	v_add_f32_e32 v94, v105, v104
	v_add_f32_e32 v94, v106, v94
	v_add_f32_e32 v94, v107, v94
	v_add_f32_e32 v67, v94, v67
	v_add_f32_e32 v94, v111, v110
	v_add_f32_e32 v94, v116, v94
	v_add_f32_e32 v94, v117, v94
	v_add_f32_e32 v67, v94, v67
	ds_bpermute_b32 v94, v69, v67
	v_pk_mul_f32 v[98:99], v[10:11], v[10:11]
	v_pk_mul_f32 v[96:97], v[16:17], v[16:17]
	v_pk_mul_f32 v[102:103], v[12:13], v[12:13]
	v_pk_mul_f32 v[104:105], v[6:7], v[6:7]
	s_waitcnt lgkmcnt(0)
	v_add_f32_e32 v67, v67, v94
	ds_bpermute_b32 v94, v73, v67
	v_pk_mul_f32 v[106:107], v[8:9], v[8:9]
	v_pk_mul_f32 v[116:117], v[2:3], v[2:3]
	s_waitcnt lgkmcnt(0)
	v_add_f32_e32 v67, v67, v94
	ds_bpermute_b32 v94, v75, v67
	s_waitcnt lgkmcnt(0)
	v_add_f32_e32 v67, v67, v94
	ds_bpermute_b32 v94, v77, v67
	s_waitcnt lgkmcnt(0)
	v_add_f32_e32 v67, v67, v94
	ds_bpermute_b32 v94, v101, v67
	s_waitcnt lgkmcnt(0)
	v_add_f32_e32 v110, v67, v94
	v_pk_mul_f32 v[94:95], v[14:15], v[14:15]
	ds_bpermute_b32 v111, v108, v110
	v_add_f32_e32 v67, v95, v94
	v_add_f32_e32 v94, v99, v98
	v_add_f32_e32 v67, v96, v67
	v_add_f32_e32 v94, v102, v94
	v_add_f32_e32 v67, v97, v67
	v_add_f32_e32 v94, v103, v94
	v_add_f32_e32 v67, v94, v67
	v_add_f32_e32 v94, v105, v104
	v_add_f32_e32 v94, v106, v94
	v_add_f32_e32 v94, v107, v94
	v_add_f32_e32 v67, v94, v67
	v_add_f32_e32 v94, v116, v117
	v_add_f32_e32 v94, v94, v118
	v_add_f32_e32 v94, v94, v119
	v_add_f32_e32 v67, v67, v94
	ds_bpermute_b32 v94, v69, v67
	s_waitcnt lgkmcnt(0)
	v_add_f32_e32 v67, v67, v94
	ds_bpermute_b32 v94, v73, v67
	s_waitcnt lgkmcnt(0)
	v_add_f32_e32 v67, v67, v94
	ds_bpermute_b32 v94, v75, v67
	s_waitcnt lgkmcnt(0)
	v_add_f32_e32 v67, v67, v94
	ds_bpermute_b32 v94, v77, v67
	s_waitcnt lgkmcnt(0)
	v_add_f32_e32 v67, v67, v94
	ds_bpermute_b32 v94, v101, v67
	s_waitcnt lgkmcnt(0)
	v_add_f32_e32 v67, v67, v94
	v_add_u32_e32 v94, 0xffffe000, v66
	v_lshrrev_b32_e32 v94, 12, v94
	v_add_u32_e32 v94, 1, v94
	v_cndmask_b32_e64 v94, 0, v94, s[0:1]
	v_readlane_b32 s0, v250, 40
	v_readlane_b32 s1, v250, 41
	v_add_u32_e32 v96, s10, v94
	ds_bpermute_b32 v109, v108, v67
	v_mov_b64_e32 v[94:95], s[0:1]
	v_mad_i64_i32 v[94:95], s[0:1], v96, s67, v[94:95]
	s_mov_b64 s[0:1], 0x3000
	s_nop 0
	v_lshl_add_u64 v[104:105], v[94:95], 0, s[0:1]
	v_cmp_gt_f32_e64 s[0:1], s54, v0
	v_mul_f32_e32 v96, 0x4b800000, v0
	s_nop 0
	v_cndmask_b32_e64 v0, v0, v96, s[0:1]
	v_rsq_f32_e32 v0, v0
	s_nop 0
	v_mul_f32_e32 v96, 0x45800000, v0
	v_cndmask_b32_e64 v100, v0, v96, s[0:1]
	s_mov_b64 s[0:1], 0x4000
	v_lshl_add_u64 v[106:107], v[94:95], 0, s[0:1]
	v_lshlrev_b32_e32 v0, 2, v68
	v_lshl_add_u64 v[98:99], v[104:105], 0, v[0:1]
	v_lshl_add_u64 v[102:103], v[106:107], 0, v[0:1]
	global_load_dwordx4 v[94:97], v[70:71], off
	global_load_dwordx4 v[124:127], v[70:71], off offset:1024
	global_load_dwordx4 v[128:131], v[98:99], off offset:1024
	global_load_dwordx4 v[132:135], v[102:103], off offset:1024
	global_load_dwordx4 v[136:139], v[70:71], off offset:2048
	global_load_dwordx4 v[140:143], v[98:99], off offset:2048
	global_load_dwordx4 v[144:147], v[102:103], off offset:2048
	global_load_dwordx4 v[148:151], v[70:71], off offset:3072
	global_load_dwordx4 v[152:155], v[98:99], off offset:3072
	global_load_dwordx4 v[156:159], v[102:103], off offset:3072
	global_load_dwordx4 v[116:119], v[98:99], off
	global_load_dwordx4 v[120:123], v[102:103], off
	v_pk_mul_f32 v[62:63], v[62:63], v[100:101] op_sel_hi:[1,0]
	v_pk_mul_f32 v[64:65], v[64:65], v[100:101] op_sel_hi:[1,0]
	s_mov_b32 s0, 0x9885000
	v_pk_mul_f32 v[58:59], v[58:59], v[100:101] op_sel_hi:[1,0]
	v_pk_mul_f32 v[60:61], v[60:61], v[100:101] op_sel_hi:[1,0]
	v_pk_mul_f32 v[54:55], v[54:55], v[100:101] op_sel_hi:[1,0]
	v_pk_mul_f32 v[56:57], v[56:57], v[100:101] op_sel_hi:[1,0]
	v_pk_mul_f32 v[50:51], v[50:51], v[100:101] op_sel_hi:[1,0]
	v_pk_mul_f32 v[52:53], v[52:53], v[100:101] op_sel_hi:[1,0]
	s_waitcnt vmcnt(2)
	v_pk_mul_f32 v[62:63], v[62:63], v[94:95]
	v_pk_mul_f32 v[64:65], v[64:65], v[96:97]
	s_waitcnt vmcnt(0)
	v_pk_add_f32 v[94:95], v[120:121], 1.0 op_sel_hi:[1,0]
	s_nop 0
	v_pk_fma_f32 v[62:63], v[62:63], v[94:95], v[116:117]
	v_pk_add_f32 v[94:95], v[122:123], 1.0 op_sel_hi:[1,0]
	v_cvt_pk_bf16_f32 v62, v62, v63
	v_pk_fma_f32 v[64:65], v[64:65], v[94:95], v[118:119]
	v_lshlrev_b32_e32 v94, 2, v72
	v_cvt_pk_bf16_f32 v63, v64, v65
	v_lshl_add_u64 v[64:65], s[94:95], 0, v[86:87]
	v_add_co_u32_e64 v102, s[0:1], s0, v64
	v_mov_b32_e32 v95, v1
	s_nop 0
	v_addc_co_u32_e64 v103, s[0:1], 0, v65, s[0:1]
	global_store_dwordx2 v[102:103], v[62:63], off offset:256
	v_lshl_add_u64 v[96:97], v[104:105], 0, v[94:95]
	v_lshl_add_u64 v[116:117], v[106:107], 0, v[94:95]
	v_mov_b64_e32 v[62:63], v[124:125]
	v_mov_b64_e32 v[64:65], v[126:127]
	s_nop 0
	v_mov_b64_e32 v[96:97], v[128:129]
	v_mov_b64_e32 v[98:99], v[130:131]
	s_nop 0
	v_mov_b64_e32 v[116:117], v[132:133]
	v_mov_b64_e32 v[118:119], v[134:135]
	v_pk_mul_f32 v[58:59], v[58:59], v[62:63]
	v_pk_mul_f32 v[60:61], v[60:61], v[64:65]
	v_pk_add_f32 v[62:63], v[116:117], 1.0 op_sel_hi:[1,0]
	s_nop 0
	v_pk_fma_f32 v[58:59], v[58:59], v[62:63], v[96:97]
	v_pk_add_f32 v[62:63], v[118:119], 1.0 op_sel_hi:[1,0]
	v_cvt_pk_bf16_f32 v58, v58, v59
	v_pk_fma_f32 v[60:61], v[60:61], v[62:63], v[98:99]
	v_lshlrev_b32_e32 v96, 2, v74
	v_cvt_pk_bf16_f32 v59, v60, v61
	v_mov_b32_e32 v97, v1
	global_store_dwordx2 v[102:103], v[58:59], off offset:768
	v_lshl_add_u64 v[62:63], v[104:105], 0, v[96:97]
	v_lshl_add_u64 v[98:99], v[106:107], 0, v[96:97]
	v_mov_b64_e32 v[58:59], v[136:137]
	v_mov_b64_e32 v[60:61], v[138:139]
	s_nop 0
	v_mov_b64_e32 v[62:63], v[140:141]
	v_mov_b64_e32 v[64:65], v[142:143]
	s_nop 0
	v_mov_b64_e32 v[116:117], v[144:145]
	v_mov_b64_e32 v[118:119], v[146:147]
	v_lshlrev_b32_e32 v98, 2, v76
	v_mov_b32_e32 v99, v1
	v_pk_mul_f32 v[54:55], v[54:55], v[58:59]
	v_pk_mul_f32 v[56:57], v[56:57], v[60:61]
	v_pk_add_f32 v[58:59], v[116:117], 1.0 op_sel_hi:[1,0]
	s_nop 0
	v_pk_fma_f32 v[54:55], v[54:55], v[58:59], v[62:63]
	v_pk_add_f32 v[58:59], v[118:119], 1.0 op_sel_hi:[1,0]
	v_cvt_pk_bf16_f32 v54, v54, v55
	v_pk_fma_f32 v[56:57], v[56:57], v[58:59], v[64:65]
	v_lshl_add_u64 v[62:63], v[106:107], 0, v[98:99]
	v_cvt_pk_bf16_f32 v55, v56, v57
	global_store_dwordx2 v[102:103], v[54:55], off offset:1280
	v_lshl_add_u64 v[54:55], v[104:105], 0, v[98:99]
	v_mov_b64_e32 v[58:59], v[148:149]
	v_mov_b64_e32 v[60:61], v[150:151]
	s_nop 0
	v_mov_b64_e32 v[54:55], v[152:153]
	v_mov_b64_e32 v[56:57], v[154:155]
	s_nop 0
	v_mov_b64_e32 v[62:63], v[156:157]
	v_mov_b64_e32 v[64:65], v[158:159]
	v_pk_mul_f32 v[50:51], v[50:51], v[58:59]
	v_pk_mul_f32 v[52:53], v[52:53], v[60:61]
	v_pk_add_f32 v[58:59], v[62:63], 1.0 op_sel_hi:[1,0]
	s_nop 0
	v_pk_fma_f32 v[50:51], v[50:51], v[58:59], v[54:55]
	v_pk_add_f32 v[54:55], v[64:65], 1.0 op_sel_hi:[1,0]
	v_cvt_pk_bf16_f32 v50, v50, v51
	v_pk_fma_f32 v[52:53], v[52:53], v[54:55], v[56:57]
	s_nop 0
	v_cvt_pk_bf16_f32 v51, v52, v53
	global_store_dwordx2 v[102:103], v[50:51], off offset:1792
	s_and_saveexec_b64 s[8:9], s[42:43]
	s_cbranch_execz .LBB0_92
	v_add_u32_e32 v50, 0xffffe000, v112
	v_lshrrev_b32_e32 v50, 12, v50
	s_movk_i32 s0, 0x1fff
	v_add_u32_e32 v50, 1, v50
	v_cmp_lt_i32_e64 s[0:1], s0, v112
	v_add_f32_e32 v56, v113, v114
	s_nop 0
	v_cndmask_b32_e64 v50, 0, v50, s[0:1]
	v_readlane_b32 s0, v250, 40
	v_readlane_b32 s1, v250, 41
	v_add_u32_e32 v52, s10, v50
	s_nop 0
	v_mov_b64_e32 v[50:51], s[0:1]
	v_mad_i64_i32 v[52:53], s[0:1], v52, s67, v[50:51]
	s_mov_b64 s[0:1], 0x3000
	v_fmamk_f32 v50, v56, 0x3a800000, v213
	v_lshl_add_u64 v[54:55], v[52:53], 0, s[0:1]
	v_cmp_gt_f32_e64 s[0:1], s54, v50
	v_mul_f32_e32 v51, 0x4b800000, v50
	v_lshl_add_u64 v[60:61], v[54:55], 0, v[0:1]
	v_cndmask_b32_e64 v50, v50, v51, s[0:1]
	v_rsq_f32_e32 v50, v50
	s_nop 0
	v_mul_f32_e32 v51, 0x45800000, v50
	v_cndmask_b32_e64 v50, v50, v51, s[0:1]
	s_mov_b64 s[0:1], 0x4000
	v_lshl_add_u64 v[52:53], v[52:53], 0, s[0:1]
	v_lshl_add_u64 v[64:65], v[52:53], 0, v[0:1]
	global_load_dwordx4 v[56:59], v[70:71], off
	s_nop 0
	global_load_dwordx4 v[124:127], v[70:71], off offset:1024
	global_load_dwordx4 v[128:131], v[60:61], off offset:1024
	global_load_dwordx4 v[132:135], v[64:65], off offset:1024
	global_load_dwordx4 v[136:139], v[70:71], off offset:2048
	global_load_dwordx4 v[140:143], v[60:61], off offset:2048
	global_load_dwordx4 v[144:147], v[64:65], off offset:2048
	global_load_dwordx4 v[148:151], v[70:71], off offset:3072
	global_load_dwordx4 v[152:155], v[60:61], off offset:3072
	global_load_dwordx4 v[156:159], v[64:65], off offset:3072
	global_load_dwordx4 v[60:63], v[60:61], off
	s_nop 0
	global_load_dwordx4 v[102:105], v[64:65], off
	v_pk_mul_f32 v[46:47], v[46:47], v[50:51] op_sel_hi:[1,0]
	v_pk_mul_f32 v[48:49], v[48:49], v[50:51] op_sel_hi:[1,0]
	s_mov_b32 s0, 0x9885000
	v_lshl_add_u64 v[64:65], v[52:53], 0, v[94:95]
	v_pk_mul_f32 v[42:43], v[42:43], v[50:51] op_sel_hi:[1,0]
	v_pk_mul_f32 v[44:45], v[44:45], v[50:51] op_sel_hi:[1,0]
	v_pk_mul_f32 v[38:39], v[38:39], v[50:51] op_sel_hi:[1,0]
	v_pk_mul_f32 v[40:41], v[40:41], v[50:51] op_sel_hi:[1,0]
	v_pk_mul_f32 v[34:35], v[34:35], v[50:51] op_sel_hi:[1,0]
	v_pk_mul_f32 v[36:37], v[36:37], v[50:51] op_sel_hi:[1,0]
	s_waitcnt vmcnt(2)
	v_pk_mul_f32 v[46:47], v[46:47], v[56:57]
	v_pk_mul_f32 v[48:49], v[48:49], v[58:59]
	s_waitcnt vmcnt(0)
	v_pk_add_f32 v[56:57], v[102:103], 1.0 op_sel_hi:[1,0]
	s_nop 0
	v_pk_fma_f32 v[46:47], v[46:47], v[56:57], v[60:61]
	v_pk_add_f32 v[56:57], v[104:105], 1.0 op_sel_hi:[1,0]
	s_nop 0
	v_pk_fma_f32 v[48:49], v[48:49], v[56:57], v[62:63]
	v_cvt_pk_bf16_f32 v56, v46, v47
	v_lshl_add_u64 v[46:47], s[94:95], 0, v[82:83]
	v_add_co_u32_e64 v46, s[0:1], s0, v46
	v_cvt_pk_bf16_f32 v57, v48, v49
	s_nop 0
	v_addc_co_u32_e64 v47, s[0:1], 0, v47, s[0:1]
	global_store_dwordx2 v[46:47], v[56:57], off offset:256
	v_lshl_add_u64 v[48:49], v[54:55], 0, v[94:95]
	v_mov_b64_e32 v[56:57], v[124:125]
	v_mov_b64_e32 v[58:59], v[126:127]
	v_mov_b64_e32 v[60:61], v[128:129]
	v_mov_b64_e32 v[62:63], v[130:131]
	v_mov_b64_e32 v[102:103], v[132:133]
	v_mov_b64_e32 v[104:105], v[134:135]
	v_pk_mul_f32 v[42:43], v[42:43], v[56:57]
	v_pk_mul_f32 v[44:45], v[44:45], v[58:59]
	v_pk_add_f32 v[48:49], v[102:103], 1.0 op_sel_hi:[1,0]
	s_nop 0
	v_pk_fma_f32 v[42:43], v[42:43], v[48:49], v[60:61]
	v_pk_add_f32 v[48:49], v[104:105], 1.0 op_sel_hi:[1,0]
	v_cvt_pk_bf16_f32 v42, v42, v43
	v_pk_fma_f32 v[44:45], v[44:45], v[48:49], v[62:63]
	v_lshl_add_u64 v[60:61], v[52:53], 0, v[96:97]
	v_cvt_pk_bf16_f32 v43, v44, v45
	global_store_dwordx2 v[46:47], v[42:43], off offset:768
	v_lshl_add_u64 v[48:49], v[54:55], 0, v[96:97]
	v_mov_b64_e32 v[42:43], v[136:137]
	v_mov_b64_e32 v[44:45], v[138:139]
	v_mov_b64_e32 v[56:57], v[140:141]
	v_mov_b64_e32 v[58:59], v[142:143]
	s_nop 0
	v_mov_b64_e32 v[60:61], v[144:145]
	v_mov_b64_e32 v[62:63], v[146:147]
	v_lshl_add_u64 v[48:49], v[52:53], 0, v[98:99]
	v_pk_mul_f32 v[38:39], v[38:39], v[42:43]
	v_pk_mul_f32 v[40:41], v[40:41], v[44:45]
	v_pk_add_f32 v[42:43], v[60:61], 1.0 op_sel_hi:[1,0]
	s_nop 0
	v_pk_fma_f32 v[38:39], v[38:39], v[42:43], v[56:57]
	v_pk_add_f32 v[42:43], v[62:63], 1.0 op_sel_hi:[1,0]
	v_cvt_pk_bf16_f32 v38, v38, v39
	v_pk_fma_f32 v[40:41], v[40:41], v[42:43], v[58:59]
	v_lshl_add_u64 v[42:43], v[54:55], 0, v[98:99]
	v_cvt_pk_bf16_f32 v39, v40, v41
	global_store_dwordx2 v[46:47], v[38:39], off offset:1280
	v_mov_b64_e32 v[38:39], v[148:149]
	v_mov_b64_e32 v[40:41], v[150:151]
	s_nop 0
	v_mov_b64_e32 v[42:43], v[152:153]
	v_mov_b64_e32 v[44:45], v[154:155]
	s_nop 0
	v_mov_b64_e32 v[52:53], v[156:157]
	v_mov_b64_e32 v[54:55], v[158:159]
	v_pk_mul_f32 v[34:35], v[34:35], v[38:39]
	v_pk_mul_f32 v[36:37], v[36:37], v[40:41]
	v_pk_add_f32 v[38:39], v[52:53], 1.0 op_sel_hi:[1,0]
	s_nop 0
	v_pk_fma_f32 v[34:35], v[34:35], v[38:39], v[42:43]
	v_pk_add_f32 v[38:39], v[54:55], 1.0 op_sel_hi:[1,0]
	v_cvt_pk_bf16_f32 v34, v34, v35
	v_pk_fma_f32 v[36:37], v[36:37], v[38:39], v[44:45]
	s_nop 0
	v_cvt_pk_bf16_f32 v35, v36, v37
	global_store_dwordx2 v[46:47], v[34:35], off offset:1792
	s_or_b64 exec, exec, s[8:9]
	s_and_saveexec_b64 s[8:9], s[40:41]
	s_cbranch_execnz .LBB0_93

.LBB0_93:
	v_add_u32_e32 v34, 0xffffe000, v92
	v_lshrrev_b32_e32 v34, 12, v34
	s_movk_i32 s0, 0x1fff
	v_add_u32_e32 v34, 1, v34
	v_cmp_lt_i32_e64 s[0:1], s0, v92
	v_add_f32_e32 v40, v110, v111
	v_lshlrev_b64 v[52:53], 11, v[92:93]
	v_cndmask_b32_e64 v34, 0, v34, s[0:1]
	v_readlane_b32 s0, v250, 40
	v_readlane_b32 s1, v250, 41
	v_add_u32_e32 v36, s10, v34
	v_mov_b32_e32 v95, v1
	v_mov_b64_e32 v[34:35], s[0:1]
	v_mad_i64_i32 v[38:39], s[0:1], v36, s67, v[34:35]
	s_mov_b64 s[0:1], 0x3000
	v_fmamk_f32 v34, v40, 0x3a800000, v213
	v_lshl_add_u64 v[36:37], v[38:39], 0, s[0:1]
	v_cmp_gt_f32_e64 s[0:1], s54, v34
	v_mul_f32_e32 v35, 0x4b800000, v34
	v_lshl_add_u64 v[44:45], v[36:37], 0, v[0:1]
	v_cndmask_b32_e64 v34, v34, v35, s[0:1]
	v_rsq_f32_e32 v34, v34
	v_mov_b32_e32 v97, v1
	v_mov_b32_e32 v99, v1
	v_mul_f32_e32 v35, 0x45800000, v34
	v_cndmask_b32_e64 v34, v34, v35, s[0:1]
	s_mov_b64 s[0:1], 0x4000
	v_lshl_add_u64 v[38:39], v[38:39], 0, s[0:1]
	v_lshl_add_u64 v[48:49], v[38:39], 0, v[0:1]
	global_load_dwordx4 v[40:43], v[70:71], off
	s_nop 0
	global_load_dwordx4 v[124:127], v[70:71], off offset:1024
	global_load_dwordx4 v[128:131], v[44:45], off offset:1024
	global_load_dwordx4 v[132:135], v[48:49], off offset:1024
	global_load_dwordx4 v[136:139], v[70:71], off offset:2048
	global_load_dwordx4 v[140:143], v[44:45], off offset:2048
	global_load_dwordx4 v[144:147], v[48:49], off offset:2048
	global_load_dwordx4 v[148:151], v[70:71], off offset:3072
	global_load_dwordx4 v[152:155], v[44:45], off offset:3072
	global_load_dwordx4 v[156:159], v[48:49], off offset:3072
	global_load_dwordx4 v[44:47], v[44:45], off
	s_nop 0
	global_load_dwordx4 v[48:51], v[48:49], off
	v_pk_mul_f32 v[30:31], v[30:31], v[34:35] op_sel_hi:[1,0]
	v_pk_mul_f32 v[32:33], v[32:33], v[34:35] op_sel_hi:[1,0]
	v_pk_mul_f32 v[26:27], v[26:27], v[34:35] op_sel_hi:[1,0]
	v_pk_mul_f32 v[28:29], v[28:29], v[34:35] op_sel_hi:[1,0]
	v_pk_mul_f32 v[22:23], v[22:23], v[34:35] op_sel_hi:[1,0]
	v_pk_mul_f32 v[24:25], v[24:25], v[34:35] op_sel_hi:[1,0]
	v_pk_mul_f32 v[18:19], v[18:19], v[34:35] op_sel_hi:[1,0]
	v_pk_mul_f32 v[20:21], v[20:21], v[34:35] op_sel_hi:[1,0]
	s_waitcnt vmcnt(2)
	v_pk_mul_f32 v[30:31], v[30:31], v[40:41]
	v_pk_mul_f32 v[32:33], v[32:33], v[42:43]
	s_waitcnt vmcnt(0)
	v_pk_add_f32 v[40:41], v[48:49], 1.0 op_sel_hi:[1,0]
	v_lshl_add_u64 v[48:49], v[38:39], 0, v[94:95]
	v_pk_fma_f32 v[30:31], v[30:31], v[40:41], v[44:45]
	v_pk_add_f32 v[40:41], v[50:51], 1.0 op_sel_hi:[1,0]
	s_nop 0
	v_pk_fma_f32 v[32:33], v[32:33], v[40:41], v[46:47]
	v_cvt_pk_bf16_f32 v40, v30, v31
	v_cvt_pk_bf16_f32 v41, v32, v33
	v_lshl_add_u64 v[30:31], v[80:81], 0, v[52:53]
	global_store_dwordx2 v[30:31], v[40:41], off
	v_lshl_add_u64 v[32:33], v[36:37], 0, v[94:95]
	v_mov_b64_e32 v[40:41], v[124:125]
	v_mov_b64_e32 v[42:43], v[126:127]
	v_mov_b64_e32 v[44:45], v[128:129]
	v_mov_b64_e32 v[46:47], v[130:131]
	s_nop 0
	v_mov_b64_e32 v[48:49], v[132:133]
	v_mov_b64_e32 v[50:51], v[134:135]
	v_pk_mul_f32 v[26:27], v[26:27], v[40:41]
	v_pk_mul_f32 v[28:29], v[28:29], v[42:43]
	v_pk_add_f32 v[32:33], v[48:49], 1.0 op_sel_hi:[1,0]
	s_nop 0
	v_pk_fma_f32 v[26:27], v[26:27], v[32:33], v[44:45]
	v_pk_add_f32 v[32:33], v[50:51], 1.0 op_sel_hi:[1,0]
	v_cvt_pk_bf16_f32 v26, v26, v27
	v_pk_fma_f32 v[28:29], v[28:29], v[32:33], v[46:47]
	v_lshl_add_u64 v[44:45], v[38:39], 0, v[96:97]
	v_cvt_pk_bf16_f32 v27, v28, v29
	global_store_dwordx2 v[30:31], v[26:27], off offset:512
	v_lshl_add_u64 v[32:33], v[36:37], 0, v[96:97]
	v_mov_b64_e32 v[26:27], v[136:137]
	v_mov_b64_e32 v[28:29], v[138:139]
	v_mov_b64_e32 v[40:41], v[140:141]
	v_mov_b64_e32 v[42:43], v[142:143]
	s_nop 0
	v_mov_b64_e32 v[44:45], v[144:145]
	v_mov_b64_e32 v[46:47], v[146:147]
	v_lshl_add_u64 v[32:33], v[38:39], 0, v[98:99]
	v_pk_mul_f32 v[22:23], v[22:23], v[26:27]
	v_pk_mul_f32 v[24:25], v[24:25], v[28:29]
	v_pk_add_f32 v[26:27], v[44:45], 1.0 op_sel_hi:[1,0]
	s_nop 0
	v_pk_fma_f32 v[22:23], v[22:23], v[26:27], v[40:41]
	v_pk_add_f32 v[26:27], v[46:47], 1.0 op_sel_hi:[1,0]
	v_cvt_pk_bf16_f32 v22, v22, v23
	v_pk_fma_f32 v[24:25], v[24:25], v[26:27], v[42:43]
	v_lshl_add_u64 v[26:27], v[36:37], 0, v[98:99]
	v_cvt_pk_bf16_f32 v23, v24, v25
	global_store_dwordx2 v[30:31], v[22:23], off offset:1024
	v_mov_b64_e32 v[22:23], v[148:149]
	v_mov_b64_e32 v[24:25], v[150:151]
	s_nop 0
	v_mov_b64_e32 v[26:27], v[152:153]
	v_mov_b64_e32 v[28:29], v[154:155]
	s_nop 0
	v_mov_b64_e32 v[36:37], v[156:157]
	v_mov_b64_e32 v[38:39], v[158:159]
	v_pk_mul_f32 v[18:19], v[18:19], v[22:23]
	v_pk_mul_f32 v[20:21], v[20:21], v[24:25]
	v_pk_add_f32 v[22:23], v[36:37], 1.0 op_sel_hi:[1,0]
	s_nop 0
	v_pk_fma_f32 v[18:19], v[18:19], v[22:23], v[26:27]
	v_pk_add_f32 v[22:23], v[38:39], 1.0 op_sel_hi:[1,0]
	v_cvt_pk_bf16_f32 v18, v18, v19
	v_pk_fma_f32 v[20:21], v[20:21], v[22:23], v[28:29]
	s_nop 0
	v_cvt_pk_bf16_f32 v19, v20, v21
	global_store_dwordx2 v[30:31], v[18:19], off offset:1536
	s_or_b64 exec, exec, s[8:9]
	s_and_saveexec_b64 s[0:1], vcc
	s_cbranch_execz .LBB0_82
.LBB0_94:
	v_add_u32_e32 v18, 0xffffe000, v90
	v_lshrrev_b32_e32 v18, 12, v18
	s_movk_i32 s8, 0x1fff
	v_add_u32_e32 v18, 1, v18
	v_cmp_lt_i32_e32 vcc, s8, v90
	v_readlane_b32 s8, v250, 40
	v_readlane_b32 s9, v250, 41
	v_cndmask_b32_e32 v18, 0, v18, vcc
	v_add_u32_e32 v20, s10, v18
	v_mov_b64_e32 v[18:19], s[8:9]
	v_mad_i64_i32 v[22:23], s[8:9], v20, s67, v[18:19]
	s_mov_b64 s[8:9], 0x3000
	s_nop 0
	v_lshl_add_u64 v[20:21], v[22:23], 0, s[8:9]
	s_mov_b64 s[8:9], 0x4000
	v_lshl_add_u64 v[22:23], v[22:23], 0, s[8:9]
	s_waitcnt lgkmcnt(0)
	v_add_f32_e32 v24, v67, v109
	v_lshl_add_u64 v[28:29], v[20:21], 0, v[0:1]
	v_lshl_add_u64 v[32:33], v[22:23], 0, v[0:1]
	v_fmamk_f32 v18, v24, 0x3a800000, v213
	global_load_dwordx4 v[24:27], v[70:71], off
	s_nop 0
	global_load_dwordx4 v[124:127], v[70:71], off offset:1024
	global_load_dwordx4 v[128:131], v[28:29], off offset:1024
	global_load_dwordx4 v[132:135], v[32:33], off offset:1024
	global_load_dwordx4 v[136:139], v[70:71], off offset:2048
	global_load_dwordx4 v[140:143], v[28:29], off offset:2048
	global_load_dwordx4 v[144:147], v[32:33], off offset:2048
	global_load_dwordx4 v[148:151], v[70:71], off offset:3072
	global_load_dwordx4 v[152:155], v[28:29], off offset:3072
	global_load_dwordx4 v[156:159], v[32:33], off offset:3072
	global_load_dwordx4 v[28:31], v[28:29], off
	s_nop 0
	global_load_dwordx4 v[32:35], v[32:33], off
	v_cmp_gt_f32_e32 vcc, s54, v18
	v_mul_f32_e32 v19, 0x4b800000, v18
	v_lshlrev_b64 v[36:37], 11, v[90:91]
	v_cndmask_b32_e32 v18, v18, v19, vcc
	v_rsq_f32_e32 v18, v18
	v_mov_b32_e32 v95, v1
	v_mov_b32_e32 v97, v1
	v_mov_b32_e32 v99, v1
	v_mul_f32_e32 v19, 0x45800000, v18
	v_cndmask_b32_e32 v18, v18, v19, vcc
	v_pk_mul_f32 v[14:15], v[14:15], v[18:19] op_sel_hi:[1,0]
	v_pk_mul_f32 v[16:17], v[16:17], v[18:19] op_sel_hi:[1,0]
	v_pk_mul_f32 v[10:11], v[10:11], v[18:19] op_sel_hi:[1,0]
	v_pk_mul_f32 v[12:13], v[12:13], v[18:19] op_sel_hi:[1,0]
	v_pk_mul_f32 v[6:7], v[6:7], v[18:19] op_sel_hi:[1,0]
	v_pk_mul_f32 v[8:9], v[8:9], v[18:19] op_sel_hi:[1,0]
	v_pk_mul_f32 v[2:3], v[2:3], v[18:19] op_sel_hi:[1,0]
	v_pk_mul_f32 v[4:5], v[4:5], v[18:19] op_sel_hi:[1,0]
	s_waitcnt vmcnt(2)
	v_pk_mul_f32 v[14:15], v[14:15], v[24:25]
	v_pk_mul_f32 v[16:17], v[16:17], v[26:27]
	s_waitcnt vmcnt(0)
	v_pk_add_f32 v[24:25], v[32:33], 1.0 op_sel_hi:[1,0]
	v_lshl_add_u64 v[32:33], v[22:23], 0, v[94:95]
	v_pk_fma_f32 v[14:15], v[14:15], v[24:25], v[28:29]
	v_pk_add_f32 v[24:25], v[34:35], 1.0 op_sel_hi:[1,0]
	s_nop 0
	v_pk_fma_f32 v[16:17], v[16:17], v[24:25], v[30:31]
	v_cvt_pk_bf16_f32 v24, v14, v15
	v_cvt_pk_bf16_f32 v25, v16, v17
	v_lshl_add_u64 v[14:15], v[80:81], 0, v[36:37]
	global_store_dwordx2 v[14:15], v[24:25], off
	v_lshl_add_u64 v[16:17], v[20:21], 0, v[94:95]
	v_mov_b64_e32 v[24:25], v[124:125]
	v_mov_b64_e32 v[26:27], v[126:127]
	v_mov_b64_e32 v[28:29], v[128:129]
	v_mov_b64_e32 v[30:31], v[130:131]
	s_nop 0
	v_mov_b64_e32 v[32:33], v[132:133]
	v_mov_b64_e32 v[34:35], v[134:135]
	v_pk_mul_f32 v[10:11], v[10:11], v[24:25]
	v_pk_mul_f32 v[12:13], v[12:13], v[26:27]
	v_pk_add_f32 v[16:17], v[32:33], 1.0 op_sel_hi:[1,0]
	s_nop 0
	v_pk_fma_f32 v[10:11], v[10:11], v[16:17], v[28:29]
	v_pk_add_f32 v[16:17], v[34:35], 1.0 op_sel_hi:[1,0]
	v_cvt_pk_bf16_f32 v10, v10, v11
	v_pk_fma_f32 v[12:13], v[12:13], v[16:17], v[30:31]
	v_lshl_add_u64 v[28:29], v[22:23], 0, v[96:97]
	v_cvt_pk_bf16_f32 v11, v12, v13
	global_store_dwordx2 v[14:15], v[10:11], off offset:512
	v_lshl_add_u64 v[16:17], v[20:21], 0, v[96:97]
	v_mov_b64_e32 v[10:11], v[136:137]
	v_mov_b64_e32 v[12:13], v[138:139]
	v_mov_b64_e32 v[24:25], v[140:141]
	v_mov_b64_e32 v[26:27], v[142:143]
	s_nop 0
	v_mov_b64_e32 v[28:29], v[144:145]
	v_mov_b64_e32 v[30:31], v[146:147]
	v_lshl_add_u64 v[16:17], v[22:23], 0, v[98:99]
	v_pk_mul_f32 v[6:7], v[6:7], v[10:11]
	v_pk_mul_f32 v[8:9], v[8:9], v[12:13]
	v_pk_add_f32 v[10:11], v[28:29], 1.0 op_sel_hi:[1,0]
	s_nop 0
	v_pk_fma_f32 v[6:7], v[6:7], v[10:11], v[24:25]
	v_pk_add_f32 v[10:11], v[30:31], 1.0 op_sel_hi:[1,0]
	v_cvt_pk_bf16_f32 v6, v6, v7
	v_pk_fma_f32 v[8:9], v[8:9], v[10:11], v[26:27]
	v_lshl_add_u64 v[10:11], v[20:21], 0, v[98:99]
	v_cvt_pk_bf16_f32 v7, v8, v9
	global_store_dwordx2 v[14:15], v[6:7], off offset:1024
	v_mov_b64_e32 v[6:7], v[148:149]
	v_mov_b64_e32 v[8:9], v[150:151]
	s_nop 0
	v_mov_b64_e32 v[10:11], v[152:153]
	v_mov_b64_e32 v[12:13], v[154:155]
	s_nop 0
	v_mov_b64_e32 v[20:21], v[156:157]
	v_mov_b64_e32 v[22:23], v[158:159]
	v_pk_mul_f32 v[2:3], v[2:3], v[6:7]
	v_pk_mul_f32 v[4:5], v[4:5], v[8:9]
	v_pk_add_f32 v[6:7], v[20:21], 1.0 op_sel_hi:[1,0]
	s_nop 0
	v_pk_fma_f32 v[2:3], v[2:3], v[6:7], v[10:11]
	v_pk_add_f32 v[6:7], v[22:23], 1.0 op_sel_hi:[1,0]
	v_cvt_pk_bf16_f32 v2, v2, v3
	v_pk_fma_f32 v[4:5], v[4:5], v[6:7], v[12:13]
	s_nop 0
	v_cvt_pk_bf16_f32 v3, v4, v5
	global_store_dwordx2 v[14:15], v[2:3], off offset:1536
	s_branch .LBB0_82

.LBB0_601:
	s_or_b64 exec, exec, s[8:9]
	s_waitcnt vmcnt(3)
	v_mov_b32_e32 v100, v63
	s_waitcnt vmcnt(2)
	v_mov_b32_e32 v101, v59
	v_mov_b32_e32 v98, v62
	v_mov_b32_e32 v99, v58
	v_pk_mul_f32 v[100:101], v[100:101], v[100:101]
	s_waitcnt vmcnt(1)
	v_mov_b32_e32 v104, v55
	v_pk_fma_f32 v[98:99], v[98:99], v[98:99], v[100:101]
	v_mov_b32_e32 v100, v64
	v_mov_b32_e32 v101, v60
	v_pk_fma_f32 v[98:99], v[100:101], v[100:101], v[98:99]
	v_mov_b32_e32 v100, v65
	v_mov_b32_e32 v101, v61
	s_waitcnt vmcnt(0)
	v_mov_b32_e32 v105, v47
	v_pk_fma_f32 v[98:99], v[100:101], v[100:101], v[98:99]
	v_mov_b32_e32 v100, v54
	v_mov_b32_e32 v101, v46
	v_pk_mul_f32 v[104:105], v[104:105], v[104:105]
	v_add_f32_e32 v81, v98, v99
	v_pk_fma_f32 v[100:101], v[100:101], v[100:101], v[104:105]
	v_mov_b32_e32 v104, v56
	v_mov_b32_e32 v105, v48
	v_pk_fma_f32 v[100:101], v[104:105], v[104:105], v[100:101]
	v_mov_b32_e32 v104, v57
	v_mov_b32_e32 v105, v49
	v_pk_fma_f32 v[100:101], v[104:105], v[104:105], v[100:101]
	v_pk_mul_f32 v[98:99], v[50:51], v[50:51]
	v_add_f32_e32 v81, v81, v100
	v_add_f32_e32 v81, v81, v101
	s_waitcnt lgkmcnt(0)
	ds_bpermute_b32 v85, v69, v81
	v_pk_mul_f32 v[104:105], v[42:43], v[42:43]
	v_pk_mul_f32 v[100:101], v[52:53], v[52:53]
	v_pk_mul_f32 v[106:107], v[44:45], v[44:45]
	v_pk_mul_f32 v[110:111], v[38:39], v[38:39]
	s_waitcnt lgkmcnt(0)
	v_add_f32_e32 v81, v81, v85
	ds_bpermute_b32 v85, v73, v81
	v_pk_mul_f32 v[112:113], v[40:41], v[40:41]
	v_pk_mul_f32 v[114:115], v[30:31], v[30:31]
	v_pk_mul_f32 v[116:117], v[32:33], v[32:33]
	s_movk_i32 s0, 0x1fff
	s_waitcnt lgkmcnt(0)
	v_add_f32_e32 v81, v81, v85
	ds_bpermute_b32 v85, v75, v81
	v_cmp_lt_i32_e32 vcc, s0, v96
	v_readlane_b32 s0, v250, 40
	v_readlane_b32 s1, v250, 41
	s_waitcnt lgkmcnt(0)
	v_add_f32_e32 v81, v81, v85
	ds_bpermute_b32 v85, v77, v81
	s_waitcnt lgkmcnt(0)
	v_add_f32_e32 v81, v81, v85
	ds_bpermute_b32 v85, v103, v81
	s_waitcnt lgkmcnt(0)
	v_add_f32_e32 v95, v81, v85
	v_add_f32_e32 v81, v99, v98
	v_add_f32_e32 v85, v105, v104
	v_add_f32_e32 v81, v100, v81
	v_add_f32_e32 v85, v106, v85
	v_add_f32_e32 v81, v101, v81
	v_add_f32_e32 v85, v107, v85
	v_add_f32_e32 v81, v85, v81
	v_add_f32_e32 v85, v111, v110
	v_add_f32_e32 v85, v112, v85
	v_add_f32_e32 v85, v113, v85
	v_add_f32_e32 v81, v85, v81
	v_add_f32_e32 v85, v115, v114
	v_add_f32_e32 v85, v116, v85
	v_add_f32_e32 v85, v117, v85
	v_add_f32_e32 v81, v85, v81
	ds_bpermute_b32 v85, v69, v81
	v_pk_mul_f32 v[98:99], v[34:35], v[34:35]
	v_pk_mul_f32 v[104:105], v[26:27], v[26:27]
	v_pk_mul_f32 v[100:101], v[36:37], v[36:37]
	v_pk_mul_f32 v[106:107], v[28:29], v[28:29]
	s_waitcnt lgkmcnt(0)
	v_add_f32_e32 v81, v81, v85
	ds_bpermute_b32 v85, v73, v81
	v_pk_mul_f32 v[110:111], v[22:23], v[22:23]
	v_pk_mul_f32 v[112:113], v[24:25], v[24:25]
	v_pk_mul_f32 v[114:115], v[2:3], v[2:3]
	v_pk_mul_f32 v[116:117], v[4:5], v[4:5]
	s_waitcnt lgkmcnt(0)
	v_add_f32_e32 v81, v81, v85
	ds_bpermute_b32 v85, v75, v81
	ds_bpermute_b32 v97, v108, v95
	s_waitcnt lgkmcnt(1)
	v_add_f32_e32 v81, v81, v85
	ds_bpermute_b32 v85, v77, v81
	s_waitcnt lgkmcnt(1)
	v_add_f32_e32 v95, v95, v97
	v_lshrrev_b32_e32 v97, 12, v80
	v_add_u32_e32 v97, 1, v97
	v_cndmask_b32_e32 v96, 0, v97, vcc
	s_waitcnt lgkmcnt(0)
	v_add_f32_e32 v81, v81, v85
	ds_bpermute_b32 v85, v103, v81
	v_fmamk_f32 v95, v95, 0x3a800000, v213
	v_cmp_gt_f32_e32 vcc, s54, v95
	s_waitcnt lgkmcnt(0)
	v_add_f32_e32 v91, v81, v85
	v_add_f32_e32 v81, v99, v98
	v_add_f32_e32 v85, v105, v104
	v_add_f32_e32 v81, v100, v81
	v_add_f32_e32 v85, v106, v85
	v_add_f32_e32 v81, v101, v81
	v_add_f32_e32 v85, v107, v85
	v_add_f32_e32 v81, v85, v81
	v_add_f32_e32 v85, v111, v110
	v_add_f32_e32 v85, v112, v85
	v_add_f32_e32 v85, v113, v85
	v_add_f32_e32 v81, v85, v81
	v_add_f32_e32 v85, v115, v114
	v_add_f32_e32 v85, v116, v85
	v_add_f32_e32 v85, v117, v85
	v_add_f32_e32 v81, v85, v81
	ds_bpermute_b32 v85, v69, v81
	v_pk_mul_f32 v[98:99], v[18:19], v[18:19]
	v_pk_mul_f32 v[104:105], v[14:15], v[14:15]
	v_pk_mul_f32 v[100:101], v[20:21], v[20:21]
	v_pk_mul_f32 v[106:107], v[16:17], v[16:17]
	s_waitcnt lgkmcnt(0)
	v_add_f32_e32 v81, v81, v85
	ds_bpermute_b32 v85, v73, v81
	v_pk_mul_f32 v[110:111], v[10:11], v[10:11]
	v_pk_mul_f32 v[112:113], v[12:13], v[12:13]
	v_pk_mul_f32 v[114:115], v[6:7], v[6:7]
	v_pk_mul_f32 v[116:117], v[8:9], v[8:9]
	s_waitcnt lgkmcnt(0)
	v_add_f32_e32 v81, v81, v85
	ds_bpermute_b32 v85, v75, v81
	ds_bpermute_b32 v93, v108, v91
	s_waitcnt lgkmcnt(1)
	v_add_f32_e32 v81, v81, v85
	ds_bpermute_b32 v85, v77, v81
	s_waitcnt lgkmcnt(0)
	v_add_f32_e32 v81, v81, v85
	ds_bpermute_b32 v85, v103, v81
	s_waitcnt lgkmcnt(0)
	v_add_f32_e32 v87, v81, v85
	v_add_f32_e32 v81, v99, v98
	v_add_f32_e32 v85, v105, v104
	v_add_u32_e32 v98, s12, v96
	v_mov_b64_e32 v[96:97], s[0:1]
	v_add_f32_e32 v81, v100, v81
	v_add_f32_e32 v85, v106, v85
	v_mad_i64_i32 v[96:97], s[0:1], v98, s67, v[96:97]
	v_mul_f32_e32 v98, 0x4b800000, v95
	v_add_f32_e32 v81, v101, v81
	v_add_f32_e32 v85, v107, v85
	v_cndmask_b32_e32 v95, v95, v98, vcc
	v_add_f32_e32 v81, v85, v81
	v_add_f32_e32 v85, v111, v110
	v_rsq_f32_e32 v95, v95
	v_add_f32_e32 v85, v112, v85
	v_add_f32_e32 v85, v113, v85
	v_add_f32_e32 v81, v85, v81
	v_add_f32_e32 v85, v114, v115
	s_mov_b64 s[0:1], 0x1000
	v_add_f32_e32 v85, v85, v116
	v_mul_f32_e32 v98, 0x45800000, v95
	v_lshl_add_u64 v[106:107], v[96:97], 0, s[0:1]
	v_add_f32_e32 v85, v85, v117
	v_cndmask_b32_e32 v102, v95, v98, vcc
	v_lshl_add_u64 v[104:105], v[96:97], 0, v[0:1]
	v_lshl_add_u64 v[100:101], v[106:107], 0, v[0:1]
	global_load_dwordx4 v[96:99], v[70:71], off
	global_load_dwordx4 v[124:127], v[70:71], off offset:1024
	global_load_dwordx4 v[128:131], v[104:105], off offset:1024
	global_load_dwordx4 v[132:135], v[100:101], off offset:1024
	global_load_dwordx4 v[136:139], v[70:71], off offset:2048
	global_load_dwordx4 v[140:143], v[104:105], off offset:2048
	global_load_dwordx4 v[144:147], v[100:101], off offset:2048
	global_load_dwordx4 v[148:151], v[70:71], off offset:3072
	global_load_dwordx4 v[152:155], v[104:105], off offset:3072
	global_load_dwordx4 v[156:159], v[100:101], off offset:3072
	global_load_dwordx4 v[110:113], v[104:105], off
	global_load_dwordx4 v[114:117], v[100:101], off
	v_pk_mul_f32 v[62:63], v[62:63], v[102:103] op_sel_hi:[1,0]
	v_pk_mul_f32 v[64:65], v[64:65], v[102:103] op_sel_hi:[1,0]
	v_pk_mul_f32 v[58:59], v[58:59], v[102:103] op_sel_hi:[1,0]
	v_pk_mul_f32 v[60:61], v[60:61], v[102:103] op_sel_hi:[1,0]
	v_pk_mul_f32 v[54:55], v[54:55], v[102:103] op_sel_hi:[1,0]
	v_pk_mul_f32 v[56:57], v[56:57], v[102:103] op_sel_hi:[1,0]
	v_add_f32_e32 v81, v81, v85
	ds_bpermute_b32 v85, v69, v81
	ds_bpermute_b32 v89, v108, v87
	v_pk_mul_f32 v[46:47], v[46:47], v[102:103] op_sel_hi:[1,0]
	v_pk_mul_f32 v[48:49], v[48:49], v[102:103] op_sel_hi:[1,0]
	s_waitcnt lgkmcnt(1)
	v_add_f32_e32 v81, v81, v85
	ds_bpermute_b32 v85, v73, v81
	s_waitcnt lgkmcnt(0)
	v_add_f32_e32 v81, v81, v85
	ds_bpermute_b32 v85, v75, v81
	s_waitcnt lgkmcnt(0)
	v_add_f32_e32 v81, v81, v85
	ds_bpermute_b32 v85, v77, v81
	s_waitcnt lgkmcnt(0)
	v_add_f32_e32 v81, v81, v85
	ds_bpermute_b32 v85, v103, v81
	s_waitcnt lgkmcnt(0)
	v_add_f32_e32 v81, v81, v85
	ds_bpermute_b32 v85, v108, v81
	s_waitcnt vmcnt(2)
	v_pk_mul_f32 v[62:63], v[62:63], v[96:97]
	v_pk_mul_f32 v[64:65], v[64:65], v[98:99]
	s_waitcnt vmcnt(0)
	v_pk_add_f32 v[96:97], v[114:115], 1.0 op_sel_hi:[1,0]
	s_nop 0
	v_pk_fma_f32 v[62:63], v[62:63], v[96:97], v[110:111]
	v_pk_add_f32 v[96:97], v[116:117], 1.0 op_sel_hi:[1,0]
	v_cvt_pk_bf16_f32 v62, v62, v63
	v_pk_fma_f32 v[64:65], v[64:65], v[96:97], v[112:113]
	v_lshlrev_b32_e32 v96, 2, v72
	v_cvt_pk_bf16_f32 v63, v64, v65
	v_mov_b32_e32 v97, v1
	global_store_dwordx2 v[82:83], v[62:63], off
	v_lshl_add_u64 v[110:111], v[106:107], 0, v[96:97]
	v_mov_b64_e32 v[62:63], v[124:125]
	v_mov_b64_e32 v[64:65], v[126:127]
	v_mov_b64_e32 v[98:99], v[128:129]
	v_mov_b64_e32 v[100:101], v[130:131]
	s_nop 0
	v_mov_b64_e32 v[110:111], v[132:133]
	v_mov_b64_e32 v[112:113], v[134:135]
	v_pk_mul_f32 v[58:59], v[58:59], v[62:63]
	v_pk_mul_f32 v[60:61], v[60:61], v[64:65]
	v_pk_add_f32 v[62:63], v[110:111], 1.0 op_sel_hi:[1,0]
	s_nop 0
	v_pk_fma_f32 v[58:59], v[58:59], v[62:63], v[98:99]
	v_pk_add_f32 v[62:63], v[112:113], 1.0 op_sel_hi:[1,0]
	v_cvt_pk_bf16_f32 v58, v58, v59
	v_pk_fma_f32 v[60:61], v[60:61], v[62:63], v[100:101]
	v_lshlrev_b32_e32 v98, 2, v74
	v_cvt_pk_bf16_f32 v59, v60, v61
	global_store_dwordx2 v[82:83], v[58:59], off offset:512
	v_mov_b32_e32 v99, v1
	v_lshl_add_u64 v[100:101], v[106:107], 0, v[98:99]
	v_mov_b64_e32 v[58:59], v[136:137]
	v_mov_b64_e32 v[60:61], v[138:139]
	v_mov_b64_e32 v[62:63], v[140:141]
	v_mov_b64_e32 v[64:65], v[142:143]
	v_mov_b64_e32 v[110:111], v[144:145]
	v_mov_b64_e32 v[112:113], v[146:147]
	v_lshlrev_b32_e32 v100, 2, v76
	v_mov_b32_e32 v101, v1
	v_pk_mul_f32 v[54:55], v[54:55], v[58:59]
	v_pk_mul_f32 v[56:57], v[56:57], v[60:61]
	v_pk_add_f32 v[58:59], v[110:111], 1.0 op_sel_hi:[1,0]
	s_nop 0
	v_pk_fma_f32 v[54:55], v[54:55], v[58:59], v[62:63]
	v_pk_add_f32 v[58:59], v[112:113], 1.0 op_sel_hi:[1,0]
	v_cvt_pk_bf16_f32 v54, v54, v55
	v_pk_fma_f32 v[56:57], v[56:57], v[58:59], v[64:65]
	v_lshl_add_u64 v[62:63], v[106:107], 0, v[100:101]
	v_cvt_pk_bf16_f32 v55, v56, v57
	global_store_dwordx2 v[82:83], v[54:55], off offset:1024
	v_mov_b64_e32 v[58:59], v[148:149]
	v_mov_b64_e32 v[60:61], v[150:151]
	s_nop 0
	v_mov_b64_e32 v[54:55], v[152:153]
	v_mov_b64_e32 v[56:57], v[154:155]
	s_nop 0
	v_mov_b64_e32 v[62:63], v[156:157]
	v_mov_b64_e32 v[64:65], v[158:159]
	v_pk_mul_f32 v[46:47], v[46:47], v[58:59]
	v_pk_mul_f32 v[48:49], v[48:49], v[60:61]
	v_pk_add_f32 v[58:59], v[62:63], 1.0 op_sel_hi:[1,0]
	s_nop 0
	v_pk_fma_f32 v[46:47], v[46:47], v[58:59], v[54:55]
	v_pk_add_f32 v[54:55], v[64:65], 1.0 op_sel_hi:[1,0]
	v_cvt_pk_bf16_f32 v46, v46, v47
	v_pk_fma_f32 v[48:49], v[48:49], v[54:55], v[56:57]
	s_nop 0
	v_cvt_pk_bf16_f32 v47, v48, v49
	global_store_dwordx2 v[82:83], v[46:47], off offset:1536
	s_and_saveexec_b64 s[0:1], s[44:45]
	s_cbranch_execz .LBB0_604
	v_lshrrev_b32_e32 v46, 12, v94
	s_movk_i32 s8, 0x1fff
	v_add_u32_e32 v46, 1, v46
	v_cmp_lt_i32_e32 vcc, s8, v92
	v_readlane_b32 s8, v250, 40
	v_readlane_b32 s9, v250, 41
	v_cndmask_b32_e32 v46, 0, v46, vcc
	v_add_u32_e32 v48, s12, v46
	v_mov_b64_e32 v[46:47], s[8:9]
	v_mad_i64_i32 v[48:49], s[8:9], v48, s67, v[46:47]
	v_add_f32_e32 v54, v91, v93
	s_mov_b64 s[8:9], 0x1000
	v_fmamk_f32 v46, v54, 0x3a800000, v213
	v_lshl_add_u64 v[54:55], v[48:49], 0, s[8:9]
	v_ashrrev_i32_e32 v93, 31, v92
	v_lshlrev_b64 v[64:65], 11, v[92:93]
	v_lshl_add_u64 v[92:93], v[54:55], 0, v[0:1]
	v_lshl_add_u64 v[48:49], v[48:49], 0, v[0:1]
	global_load_dwordx4 v[56:59], v[70:71], off
	global_load_dwordx4 v[124:127], v[70:71], off offset:1024
	global_load_dwordx4 v[128:131], v[48:49], off offset:1024
	global_load_dwordx4 v[132:135], v[92:93], off offset:1024
	global_load_dwordx4 v[136:139], v[70:71], off offset:2048
	global_load_dwordx4 v[140:143], v[48:49], off offset:2048
	global_load_dwordx4 v[144:147], v[92:93], off offset:2048
	global_load_dwordx4 v[148:151], v[70:71], off offset:3072
	global_load_dwordx4 v[152:155], v[48:49], off offset:3072
	global_load_dwordx4 v[156:159], v[92:93], off offset:3072
	global_load_dwordx4 v[60:63], v[48:49], off
	s_nop 0
	global_load_dwordx4 v[92:95], v[92:93], off
	v_cmp_gt_f32_e32 vcc, s54, v46
	v_mul_f32_e32 v47, 0x4b800000, v46
	s_nop 0
	v_cndmask_b32_e32 v46, v46, v47, vcc
	v_rsq_f32_e32 v46, v46
	s_nop 0
	v_mul_f32_e32 v47, 0x45800000, v46
	v_cndmask_b32_e32 v46, v46, v47, vcc
	v_pk_mul_f32 v[50:51], v[50:51], v[46:47] op_sel_hi:[1,0]
	v_pk_mul_f32 v[52:53], v[52:53], v[46:47] op_sel_hi:[1,0]
	v_pk_mul_f32 v[42:43], v[42:43], v[46:47] op_sel_hi:[1,0]
	v_pk_mul_f32 v[44:45], v[44:45], v[46:47] op_sel_hi:[1,0]
	v_pk_mul_f32 v[38:39], v[38:39], v[46:47] op_sel_hi:[1,0]
	v_pk_mul_f32 v[40:41], v[40:41], v[46:47] op_sel_hi:[1,0]
	v_pk_mul_f32 v[30:31], v[30:31], v[46:47] op_sel_hi:[1,0]
	v_pk_mul_f32 v[32:33], v[32:33], v[46:47] op_sel_hi:[1,0]
	s_waitcnt vmcnt(2)
	v_pk_mul_f32 v[50:51], v[50:51], v[56:57]
	v_pk_mul_f32 v[52:53], v[52:53], v[58:59]
	s_waitcnt vmcnt(0)
	v_pk_add_f32 v[56:57], v[92:93], 1.0 op_sel_hi:[1,0]
	s_nop 0
	v_pk_fma_f32 v[50:51], v[50:51], v[56:57], v[60:61]
	v_pk_add_f32 v[56:57], v[94:95], 1.0 op_sel_hi:[1,0]
	s_nop 0
	v_pk_fma_f32 v[52:53], v[52:53], v[56:57], v[62:63]
	v_cvt_pk_bf16_f32 v56, v50, v51
	v_cvt_pk_bf16_f32 v57, v52, v53
	v_lshl_add_u64 v[50:51], v[78:79], 0, v[64:65]
	global_store_dwordx2 v[50:51], v[56:57], off
	v_lshl_add_u64 v[52:53], v[54:55], 0, v[96:97]
	v_mov_b64_e32 v[56:57], v[124:125]
	v_mov_b64_e32 v[58:59], v[126:127]
	v_mov_b64_e32 v[60:61], v[128:129]
	v_mov_b64_e32 v[62:63], v[130:131]
	v_mov_b64_e32 v[92:93], v[132:133]
	v_mov_b64_e32 v[94:95], v[134:135]
	v_pk_mul_f32 v[42:43], v[42:43], v[56:57]
	v_pk_mul_f32 v[44:45], v[44:45], v[58:59]
	v_pk_add_f32 v[52:53], v[92:93], 1.0 op_sel_hi:[1,0]
	s_nop 0
	v_pk_fma_f32 v[42:43], v[42:43], v[52:53], v[60:61]
	v_pk_add_f32 v[52:53], v[94:95], 1.0 op_sel_hi:[1,0]
	v_cvt_pk_bf16_f32 v42, v42, v43
	v_pk_fma_f32 v[44:45], v[44:45], v[52:53], v[62:63]
	v_lshl_add_u64 v[52:53], v[54:55], 0, v[98:99]
	v_cvt_pk_bf16_f32 v43, v44, v45
	global_store_dwordx2 v[50:51], v[42:43], off offset:512
	v_mov_b64_e32 v[42:43], v[136:137]
	v_mov_b64_e32 v[44:45], v[138:139]
	s_nop 0
	v_mov_b64_e32 v[56:57], v[140:141]
	v_mov_b64_e32 v[58:59], v[142:143]
	v_mov_b64_e32 v[60:61], v[144:145]
	v_mov_b64_e32 v[62:63], v[146:147]
	v_lshl_add_u64 v[52:53], v[54:55], 0, v[100:101]
	v_pk_mul_f32 v[38:39], v[38:39], v[42:43]
	v_pk_mul_f32 v[40:41], v[40:41], v[44:45]
	v_pk_add_f32 v[42:43], v[60:61], 1.0 op_sel_hi:[1,0]
	s_nop 0
	v_pk_fma_f32 v[38:39], v[38:39], v[42:43], v[56:57]
	v_pk_add_f32 v[42:43], v[62:63], 1.0 op_sel_hi:[1,0]
	v_cvt_pk_bf16_f32 v38, v38, v39
	v_pk_fma_f32 v[40:41], v[40:41], v[42:43], v[58:59]
	s_nop 0
	v_cvt_pk_bf16_f32 v39, v40, v41
	global_store_dwordx2 v[50:51], v[38:39], off offset:1024
	v_mov_b64_e32 v[38:39], v[148:149]
	v_mov_b64_e32 v[40:41], v[150:151]
	s_nop 0
	v_mov_b64_e32 v[42:43], v[152:153]
	v_mov_b64_e32 v[44:45], v[154:155]
	s_nop 0
	v_mov_b64_e32 v[52:53], v[156:157]
	v_mov_b64_e32 v[54:55], v[158:159]
	v_pk_mul_f32 v[30:31], v[30:31], v[38:39]
	v_pk_mul_f32 v[32:33], v[32:33], v[40:41]
	v_pk_add_f32 v[38:39], v[52:53], 1.0 op_sel_hi:[1,0]
	s_nop 0
	v_pk_fma_f32 v[30:31], v[30:31], v[38:39], v[42:43]
	v_pk_add_f32 v[38:39], v[54:55], 1.0 op_sel_hi:[1,0]
	v_cvt_pk_bf16_f32 v30, v30, v31
	v_pk_fma_f32 v[32:33], v[32:33], v[38:39], v[44:45]
	s_nop 0
	v_cvt_pk_bf16_f32 v31, v32, v33
	global_store_dwordx2 v[50:51], v[30:31], off offset:1536
	s_or_b64 exec, exec, s[0:1]
	s_and_saveexec_b64 s[0:1], s[42:43]
	s_cbranch_execnz .LBB0_605

.LBB0_605:
	v_lshrrev_b32_e32 v30, 12, v90
	s_movk_i32 s8, 0x1fff
	v_add_u32_e32 v30, 1, v30
	v_cmp_lt_i32_e32 vcc, s8, v88
	v_readlane_b32 s8, v250, 40
	v_readlane_b32 s9, v250, 41
	v_cndmask_b32_e32 v30, 0, v30, vcc
	v_add_u32_e32 v32, s12, v30
	v_mov_b64_e32 v[30:31], s[8:9]
	v_mad_i64_i32 v[32:33], s[8:9], v32, s67, v[30:31]
	s_mov_b64 s[8:9], 0x1000
	v_add_f32_e32 v38, v87, v89
	v_lshl_add_u64 v[40:41], v[32:33], 0, s[8:9]
	v_fmamk_f32 v30, v38, 0x3a800000, v213
	v_lshl_add_u64 v[38:39], v[32:33], 0, v[0:1]
	v_lshl_add_u64 v[32:33], v[40:41], 0, v[0:1]
	global_load_dwordx4 v[42:45], v[70:71], off
	global_load_dwordx4 v[124:127], v[70:71], off offset:1024
	global_load_dwordx4 v[128:131], v[38:39], off offset:1024
	global_load_dwordx4 v[132:135], v[32:33], off offset:1024
	global_load_dwordx4 v[136:139], v[70:71], off offset:2048
	global_load_dwordx4 v[140:143], v[38:39], off offset:2048
	global_load_dwordx4 v[144:147], v[32:33], off offset:2048
	global_load_dwordx4 v[148:151], v[70:71], off offset:3072
	global_load_dwordx4 v[152:155], v[38:39], off offset:3072
	global_load_dwordx4 v[156:159], v[32:33], off offset:3072
	global_load_dwordx4 v[46:49], v[38:39], off
	global_load_dwordx4 v[50:53], v[32:33], off
	v_cmp_gt_f32_e32 vcc, s54, v30
	v_mul_f32_e32 v31, 0x4b800000, v30
	v_ashrrev_i32_e32 v89, 31, v88
	v_cndmask_b32_e32 v30, v30, v31, vcc
	v_rsq_f32_e32 v30, v30
	v_lshlrev_b64 v[54:55], 11, v[88:89]
	v_mov_b32_e32 v97, v1
	v_mov_b32_e32 v99, v1
	v_mul_f32_e32 v31, 0x45800000, v30
	v_cndmask_b32_e32 v30, v30, v31, vcc
	v_pk_mul_f32 v[32:33], v[34:35], v[30:31] op_sel_hi:[1,0]
	v_pk_mul_f32 v[26:27], v[26:27], v[30:31] op_sel_hi:[1,0]
	v_pk_mul_f32 v[28:29], v[28:29], v[30:31] op_sel_hi:[1,0]
	v_pk_mul_f32 v[22:23], v[22:23], v[30:31] op_sel_hi:[1,0]
	v_pk_mul_f32 v[24:25], v[24:25], v[30:31] op_sel_hi:[1,0]
	v_mov_b32_e32 v101, v1
	v_pk_mul_f32 v[2:3], v[2:3], v[30:31] op_sel_hi:[1,0]
	v_pk_mul_f32 v[4:5], v[4:5], v[30:31] op_sel_hi:[1,0]
	s_waitcnt vmcnt(2)
	v_pk_mul_f32 v[32:33], v[32:33], v[42:43]
	s_waitcnt vmcnt(0)
	v_pk_add_f32 v[34:35], v[50:51], 1.0 op_sel_hi:[1,0]
	s_nop 0
	v_pk_fma_f32 v[32:33], v[32:33], v[34:35], v[46:47]
	v_pk_mul_f32 v[34:35], v[36:37], v[30:31] op_sel_hi:[1,0]
	v_pk_add_f32 v[36:37], v[52:53], 1.0 op_sel_hi:[1,0]
	v_pk_mul_f32 v[34:35], v[34:35], v[44:45]
	v_lshl_add_u64 v[46:47], v[40:41], 0, v[96:97]
	v_pk_fma_f32 v[34:35], v[34:35], v[36:37], v[48:49]
	v_cvt_pk_bf16_f32 v36, v32, v33
	v_cvt_pk_bf16_f32 v37, v34, v35
	v_lshl_add_u64 v[32:33], v[78:79], 0, v[54:55]
	global_store_dwordx2 v[32:33], v[36:37], off
	v_mov_b64_e32 v[34:35], v[124:125]
	v_mov_b64_e32 v[36:37], v[126:127]
	s_nop 0
	v_mov_b64_e32 v[42:43], v[128:129]
	v_mov_b64_e32 v[44:45], v[130:131]
	s_nop 0
	v_mov_b64_e32 v[46:47], v[132:133]
	v_mov_b64_e32 v[48:49], v[134:135]
	v_pk_mul_f32 v[26:27], v[26:27], v[34:35]
	v_pk_mul_f32 v[28:29], v[28:29], v[36:37]
	v_pk_add_f32 v[34:35], v[46:47], 1.0 op_sel_hi:[1,0]
	s_nop 0
	v_pk_fma_f32 v[26:27], v[26:27], v[34:35], v[42:43]
	v_pk_add_f32 v[34:35], v[48:49], 1.0 op_sel_hi:[1,0]
	v_cvt_pk_bf16_f32 v26, v26, v27
	v_pk_fma_f32 v[28:29], v[28:29], v[34:35], v[44:45]
	v_lshl_add_u64 v[42:43], v[40:41], 0, v[98:99]
	v_cvt_pk_bf16_f32 v27, v28, v29
	global_store_dwordx2 v[32:33], v[26:27], off offset:512
	v_mov_b64_e32 v[26:27], v[136:137]
	v_mov_b64_e32 v[28:29], v[138:139]
	s_nop 0
	v_mov_b64_e32 v[34:35], v[140:141]
	v_mov_b64_e32 v[36:37], v[142:143]
	s_nop 0
	v_mov_b64_e32 v[42:43], v[144:145]
	v_mov_b64_e32 v[44:45], v[146:147]
	v_pk_mul_f32 v[22:23], v[22:23], v[26:27]
	v_pk_mul_f32 v[24:25], v[24:25], v[28:29]
	v_pk_add_f32 v[26:27], v[42:43], 1.0 op_sel_hi:[1,0]
	s_nop 0
	v_pk_fma_f32 v[22:23], v[22:23], v[26:27], v[34:35]
	v_pk_add_f32 v[26:27], v[44:45], 1.0 op_sel_hi:[1,0]
	v_cvt_pk_bf16_f32 v22, v22, v23
	v_pk_fma_f32 v[24:25], v[24:25], v[26:27], v[36:37]
	v_lshl_add_u64 v[34:35], v[40:41], 0, v[100:101]
	v_cvt_pk_bf16_f32 v23, v24, v25
	global_store_dwordx2 v[32:33], v[22:23], off offset:1024
	v_mov_b64_e32 v[22:23], v[148:149]
	v_mov_b64_e32 v[24:25], v[150:151]
	s_nop 0
	v_mov_b64_e32 v[26:27], v[152:153]
	v_mov_b64_e32 v[28:29], v[154:155]
	s_nop 0
	v_mov_b64_e32 v[34:35], v[156:157]
	v_mov_b64_e32 v[36:37], v[158:159]
	v_pk_mul_f32 v[2:3], v[2:3], v[22:23]
	v_pk_mul_f32 v[4:5], v[4:5], v[24:25]
	v_pk_add_f32 v[22:23], v[34:35], 1.0 op_sel_hi:[1,0]
	s_nop 0
	v_pk_fma_f32 v[2:3], v[2:3], v[22:23], v[26:27]
	v_pk_add_f32 v[22:23], v[36:37], 1.0 op_sel_hi:[1,0]
	v_cvt_pk_bf16_f32 v2, v2, v3
	v_pk_fma_f32 v[4:5], v[4:5], v[22:23], v[28:29]
	s_nop 0
	v_cvt_pk_bf16_f32 v3, v4, v5
	global_store_dwordx2 v[32:33], v[2:3], off offset:1536
	s_or_b64 exec, exec, s[0:1]
	s_and_saveexec_b64 s[0:1], s[40:41]
	s_cbranch_execz .LBB0_564
.LBB0_606:
	v_lshrrev_b32_e32 v2, 12, v86
	s_movk_i32 s8, 0x1fff
	v_add_u32_e32 v2, 1, v2
	v_cmp_lt_i32_e32 vcc, s8, v84
	v_readlane_b32 s8, v250, 40
	v_readlane_b32 s9, v250, 41
	v_cndmask_b32_e32 v2, 0, v2, vcc
	v_add_u32_e32 v4, s12, v2
	v_mov_b64_e32 v[2:3], s[8:9]
	v_mad_i64_i32 v[26:27], s[8:9], v4, s67, v[2:3]
	s_mov_b64 s[8:9], 0x1000
	s_nop 0
	v_lshl_add_u64 v[30:31], v[26:27], 0, s[8:9]
	v_lshl_add_u64 v[22:23], v[30:31], 0, v[0:1]
	global_load_dwordx4 v[2:5], v[70:71], off
	v_lshl_add_u64 v[32:33], v[26:27], 0, v[0:1]
	global_load_dwordx4 v[124:127], v[70:71], off offset:1024
	global_load_dwordx4 v[128:131], v[32:33], off offset:1024
	global_load_dwordx4 v[132:135], v[22:23], off offset:1024
	global_load_dwordx4 v[136:139], v[70:71], off offset:2048
	global_load_dwordx4 v[140:143], v[32:33], off offset:2048
	global_load_dwordx4 v[144:147], v[22:23], off offset:2048
	global_load_dwordx4 v[148:151], v[70:71], off offset:3072
	global_load_dwordx4 v[152:155], v[32:33], off offset:3072
	global_load_dwordx4 v[156:159], v[22:23], off offset:3072
	global_load_dwordx4 v[22:25], v[22:23], off
	s_waitcnt lgkmcnt(0)
	v_add_f32_e32 v0, v81, v85
	global_load_dwordx4 v[26:29], v[32:33], off
	v_fmamk_f32 v0, v0, 0x3a800000, v213
	v_mul_f32_e32 v34, 0x4b800000, v0
	v_cmp_gt_f32_e32 vcc, s54, v0
	v_ashrrev_i32_e32 v85, 31, v84
	v_mov_b32_e32 v97, v1
	v_cndmask_b32_e32 v0, v0, v34, vcc
	v_rsq_f32_e32 v0, v0
	v_lshlrev_b64 v[34:35], 11, v[84:85]
	v_lshl_add_u64 v[34:35], v[78:79], 0, v[34:35]
	v_lshl_add_u64 v[36:37], v[30:31], 0, v[96:97]
	v_mul_f32_e32 v38, 0x45800000, v0
	v_cndmask_b32_e32 v0, v0, v38, vcc
	v_pk_mul_f32 v[18:19], v[18:19], v[0:1] op_sel_hi:[1,0]
	v_pk_mul_f32 v[20:21], v[20:21], v[0:1] op_sel_hi:[1,0]
	v_pk_mul_f32 v[14:15], v[14:15], v[0:1] op_sel_hi:[1,0]
	v_pk_mul_f32 v[16:17], v[16:17], v[0:1] op_sel_hi:[1,0]
	v_mov_b32_e32 v99, v1
	v_pk_mul_f32 v[10:11], v[10:11], v[0:1] op_sel_hi:[1,0]
	v_pk_mul_f32 v[12:13], v[12:13], v[0:1] op_sel_hi:[1,0]
	v_mov_b32_e32 v101, v1
	v_pk_mul_f32 v[6:7], v[6:7], v[0:1] op_sel_hi:[1,0]
	v_pk_mul_f32 v[8:9], v[8:9], v[0:1] op_sel_hi:[1,0]
	s_waitcnt vmcnt(2)
	v_pk_mul_f32 v[2:3], v[18:19], v[2:3]
	v_pk_mul_f32 v[4:5], v[20:21], v[4:5]
	s_waitcnt vmcnt(1)
	v_pk_add_f32 v[18:19], v[22:23], 1.0 op_sel_hi:[1,0]
	v_pk_add_f32 v[20:21], v[24:25], 1.0 op_sel_hi:[1,0]
	s_waitcnt vmcnt(0)
	v_pk_fma_f32 v[2:3], v[2:3], v[18:19], v[26:27]
	v_pk_fma_f32 v[4:5], v[4:5], v[20:21], v[28:29]
	v_cvt_pk_bf16_f32 v2, v2, v3
	v_cvt_pk_bf16_f32 v3, v4, v5
	global_store_dwordx2 v[34:35], v[2:3], off
	v_mov_b64_e32 v[2:3], v[124:125]
	v_mov_b64_e32 v[4:5], v[126:127]
	s_nop 0
	v_mov_b64_e32 v[18:19], v[132:133]
	v_mov_b64_e32 v[20:21], v[134:135]
	v_mov_b64_e32 v[22:23], v[128:129]
	v_mov_b64_e32 v[24:25], v[130:131]
	v_lshl_add_u64 v[26:27], v[30:31], 0, v[98:99]
	v_pk_mul_f32 v[2:3], v[14:15], v[2:3]
	v_pk_add_f32 v[14:15], v[18:19], 1.0 op_sel_hi:[1,0]
	v_pk_mul_f32 v[4:5], v[16:17], v[4:5]
	v_pk_add_f32 v[16:17], v[20:21], 1.0 op_sel_hi:[1,0]
	v_pk_fma_f32 v[2:3], v[2:3], v[14:15], v[22:23]
	v_pk_fma_f32 v[4:5], v[4:5], v[16:17], v[24:25]
	v_cvt_pk_bf16_f32 v2, v2, v3
	v_cvt_pk_bf16_f32 v3, v4, v5
	global_store_dwordx2 v[34:35], v[2:3], off offset:512
	v_mov_b64_e32 v[2:3], v[136:137]
	v_mov_b64_e32 v[4:5], v[138:139]
	s_nop 0
	v_mov_b64_e32 v[14:15], v[144:145]
	v_mov_b64_e32 v[16:17], v[146:147]
	v_mov_b64_e32 v[18:19], v[140:141]
	v_mov_b64_e32 v[20:21], v[142:143]
	v_lshl_add_u64 v[22:23], v[30:31], 0, v[100:101]
	v_pk_mul_f32 v[2:3], v[10:11], v[2:3]
	v_pk_add_f32 v[10:11], v[14:15], 1.0 op_sel_hi:[1,0]
	v_pk_mul_f32 v[4:5], v[12:13], v[4:5]
	v_pk_add_f32 v[12:13], v[16:17], 1.0 op_sel_hi:[1,0]
	v_pk_fma_f32 v[2:3], v[2:3], v[10:11], v[18:19]
	v_pk_fma_f32 v[4:5], v[4:5], v[12:13], v[20:21]
	v_cvt_pk_bf16_f32 v2, v2, v3
	v_cvt_pk_bf16_f32 v3, v4, v5
	global_store_dwordx2 v[34:35], v[2:3], off offset:1024
	v_mov_b64_e32 v[2:3], v[148:149]
	v_mov_b64_e32 v[4:5], v[150:151]
	s_nop 0
	v_mov_b64_e32 v[10:11], v[156:157]
	v_mov_b64_e32 v[12:13], v[158:159]
	v_mov_b64_e32 v[14:15], v[152:153]
	v_mov_b64_e32 v[16:17], v[154:155]
	v_pk_mul_f32 v[2:3], v[6:7], v[2:3]
	v_pk_add_f32 v[6:7], v[10:11], 1.0 op_sel_hi:[1,0]
	v_pk_mul_f32 v[4:5], v[8:9], v[4:5]
	v_pk_add_f32 v[8:9], v[12:13], 1.0 op_sel_hi:[1,0]
	v_pk_fma_f32 v[2:3], v[2:3], v[6:7], v[14:15]
	v_pk_fma_f32 v[4:5], v[4:5], v[8:9], v[16:17]
	v_cvt_pk_bf16_f32 v2, v2, v3
	v_cvt_pk_bf16_f32 v3, v4, v5
	global_store_dwordx2 v[34:35], v[2:3], off offset:1536
	s_branch .LBB0_564

.LBB0_614:
	v_readlane_b32 s2, v252, 23
	v_readlane_b32 s3, v252, 24
	v_readlane_b32 s4, v252, 20
	s_nop 3
	global_load_dword v0, v1, s[2:3] sc1
	global_load_dword v2, v1, s[2:3] offset:256 sc1
	global_load_dword v3, v1, s[2:3] offset:512 sc1
	global_load_dword v4, v1, s[2:3] offset:768 sc1
	global_load_dword v5, v1, s[2:3] offset:1024 sc1
	global_load_dword v6, v1, s[2:3] offset:1280 sc1
	global_load_dword v7, v1, s[2:3] offset:1536 sc1
	global_load_dword v8, v1, s[2:3] offset:1792 sc1
	global_load_dword v9, v1, s[2:3] offset:2048 sc1
	global_load_dword v10, v1, s[2:3] offset:2304 sc1
	global_load_dword v11, v1, s[2:3] offset:2560 sc1
	global_load_dword v12, v1, s[2:3] offset:2816 sc1
	global_load_dword v13, v1, s[2:3] offset:3072 sc1
	global_load_dword v14, v1, s[2:3] offset:3328 sc1
	global_load_dword v15, v1, s[2:3] offset:3584 sc1
	global_load_dword v16, v1, s[2:3] offset:3840 sc1
	s_waitcnt vmcnt(0) lgkmcnt(0)
	s_mov_b64 s[2:3], -1
	v_add_u32_e32 v17, v2, v0
	v_add_u32_e32 v17, v17, v3
	v_add_u32_e32 v17, v17, v4
	v_add_u32_e32 v17, v17, v5
	v_add_u32_e32 v17, v17, v6
	v_add_u32_e32 v17, v17, v7
	v_add_u32_e32 v17, v17, v8
	v_add_u32_e32 v17, v17, v9
	v_add_u32_e32 v17, v17, v10
	v_add_u32_e32 v17, v17, v11
	v_add_u32_e32 v17, v17, v12
	v_add_u32_e32 v17, v17, v13
	v_add_u32_e32 v17, v17, v14
	v_add_u32_e32 v17, v17, v15
	v_add_u32_e32 v17, v17, v16
	v_cmp_eq_u32_e32 vcc, s4, v17
	s_mov_b64 s[4:5], -1
	s_cbranch_vccnz .LBB0_613
	s_and_b32 s2, s8, 0xff
	s_cmp_eq_u32 s2, 0
	s_mov_b64 s[2:3], -1
	s_mov_b64 s[6:7], -1
	s_sleep 1
	s_cbranch_scc1 .LBB0_618
	s_and_b64 vcc, exec, s[6:7]
	s_cbranch_vccz .LBB0_613
